# lnpass-in-phase-6 version, scan workgroups poll both arrival counters in one round trip
# speedup vs baseline: 1.0015x; 1.0015x over previous
;     __device__ __forceinline__ unsigned char* ws() const { return (unsigned char*)ptr(37); }
; #define ws (p.ws())
; __device__ __forceinline__ void sub_barrier(const Ctx& p, unsigned n) {
;     asm volatile("s_waitcnt vmcnt(0)" ::: "memory");
;     __syncthreads();
;     if (threadIdx.x == 0) {
;         unsigned* c = (unsigned*)(p.ws() + WS_CTR) + 128;
;         __builtin_amdgcn_fence(__ATOMIC_RELEASE, "agent");
;         asm volatile("s_waitcnt vmcnt(0)" ::: "memory");
;         __hip_atomic_fetch_add(c, 1u, __ATOMIC_RELAXED, __HIP_MEMORY_SCOPE_AGENT);
;         while (__hip_atomic_load(c, __ATOMIC_RELAXED, __HIP_MEMORY_SCOPE_AGENT) < n) __builtin_amdgcn_s_sleep(20);
;         __builtin_amdgcn_fence(__ATOMIC_ACQUIRE, "agent");
;         asm volatile("s_waitcnt vmcnt(0)" ::: "memory");
;     }
;     __syncthreads();
; }
.Lln_w1_s:
	global_load_dword v1, v0, s[4:5] offset:0 sc1
	global_load_dword v2, v0, s[4:5] offset:32 sc1
	s_waitcnt vmcnt(0)
	v_min_u32_e32 v1, v1, v2
	v_cmp_gt_u32_e32 vcc, 0x80, v1
	s_cbranch_vccz .Lln_w1_ok
	s_sleep 2
	s_branch .Lln_w1_s
